# attention: barrier A' (K-reads-done) moved from after QK MFMA 18 to after MFMA 20; 8 softmax VALU moved from high-priority to low-priority segment
# baseline (speedup 1.0000x reference)
; #define KISSUE(k0) do { const char* kp_ = Kc + (size_t)(k0) * 384; _Pragma("unroll") for (int e = 0; e < 6; ++e) \
;       __builtin_amdgcn_global_load_lds((const unsigned*)(kp_ + ksrc[e]), (unsigned*)(K_lds + (wu * 6 + e) * 1024), 16, 0, 0); } while (0)
; #define ABAR() do { asm volatile("s_waitcnt vmcnt(0) lgkmcnt(0)" ::: "memory"); __builtin_amdgcn_s_barrier(); } while (0)
; DEVI void finishSM(f32x16& p0, f32x16& p1, float alpha, float& l_reg, bf16x8& pa0, bf16x8& pa1, bf16x8& pa2, bf16x8& pa3) {
;   float ps = 0;
; #pragma unroll
;   for (int r = 0; r < 16; ++r) ps += p0[r];
; #pragma unroll
;   for (int r = 0; r < 16; ++r) ps += p1[r];
;   { auto rr = __builtin_amdgcn_permlane32_swap(__float_as_uint(ps), __float_as_uint(ps), false, false);
;     ps = __uint_as_float(rr[0]) + __uint_as_float(rr[1]); }
;   l_reg = l_reg * alpha + ps;
;     ...
;   PK4(p0, 0, pa0); PK4(p0, 8, pa1); PK4(p1, 0, pa2); PK4(p1, 8, pa3);
; template <bool FIXED>
; DEVI void attn_task(const bf16_t* __restrict__ Qb, const bf16_t* __restrict__ Kh, const bf16_t* __restrict__ Vh, bf16_t* __restrict__ Ob, char* lds, float shiftC) {
;     ...
;   for (int j = 0; j < NT; ++j) {
;     f32x16 p0 = {}, p1 = {};
; #pragma unroll
;     for (int d0 = 0; d0 < 12; ++d0) {
;       const bf16x8 b0 = *(const bf16x8*)(Kr0 + (d0 >> 2) * 128 + kx[d0 & 3]);
;       const bf16x8 b1 = *(const bf16x8*)(Kr0 + 32 * 384 + (d0 >> 2) * 128 + kx[d0 & 3]);
;       p0 = __builtin_amdgcn_mfma_f32_32x32x16_bf16(b0, qr[d0], p0, 0, 0, 0);
;       p1 = __builtin_amdgcn_mfma_f32_32x32x16_bf16(b1, qr[d0], p1, 0, 0, 0);
;     }
;     ABAR();
;     if (j + 1 < NT) KISSUE((j + 1) * 64);
;     float mn, alpha = 1.f;
;     if constexpr (FIXED) {
; #pragma unroll
;       for (int r = 0; r < 16; ++r) p0[r] = __builtin_amdgcn_exp2f(p0[r]);
; #pragma unroll
;       for (int r = 0; r < 16; ++r) p1[r] = __builtin_amdgcn_exp2f(p1[r]);
.Lat7_top:
	s_waitcnt lgkmcnt(5)
	v_mfma_f32_32x32x16_bf16 v[210:225], v[186:189], v[142:145], 0
	ds_read_b128 v[186:189], v179 offset:128
	v_exp_f32_e32 v66, v66
	v_exp_f32_e32 v67, v67
	v_exp_f32_e32 v68, v68
	v_exp_f32_e32 v69, v69
	s_waitcnt lgkmcnt(5)
	v_mfma_f32_32x32x16_bf16 v[210:225], v[190:193], v[138:141], v[210:225]
	ds_read_b128 v[190:193], v178 offset:128
	v_exp_f32_e32 v70, v70
	v_add_f32_e32 v182, 0, v66
	v_exp_f32_e32 v71, v71
	v_add_f32_e32 v182, v67, v182
	s_waitcnt lgkmcnt(5)
	v_mfma_f32_32x32x16_bf16 v[210:225], v[194:197], v[134:137], v[210:225]
	ds_read_b128 v[194:197], v181 offset:256
	v_exp_f32_e32 v72, v72
	v_add_f32_e32 v182, v68, v182
	v_exp_f32_e32 v73, v73
	v_add_f32_e32 v182, v69, v182
	s_waitcnt lgkmcnt(5)
	v_mfma_f32_32x32x16_bf16 v[210:225], v[198:201], v[126:129], v[210:225]
	ds_read_b128 v[198:201], v180 offset:256
	v_exp_f32_e32 v74, v74
	v_add_f32_e32 v182, v70, v182
	v_exp_f32_e32 v75, v75
	v_add_f32_e32 v182, v71, v182
	s_waitcnt lgkmcnt(5)
	v_mfma_f32_32x32x16_bf16 v[210:225], v[202:205], v[130:133], v[210:225]
	ds_read_b128 v[202:205], v179 offset:256
	v_exp_f32_e32 v76, v76
	v_add_f32_e32 v182, v72, v182
	v_exp_f32_e32 v77, v77
	v_add_f32_e32 v182, v73, v182
	s_waitcnt lgkmcnt(5)
	v_mfma_f32_32x32x16_bf16 v[210:225], v[206:209], v[118:121], v[210:225]
	ds_read_b128 v[206:209], v178 offset:256
	v_exp_f32_e32 v78, v78
	v_add_f32_e32 v182, v74, v182
	v_exp_f32_e32 v79, v79
	v_add_f32_e32 v182, v75, v182
	s_waitcnt lgkmcnt(5)
	v_mfma_f32_32x32x16_bf16 v[210:225], v[186:189], v[122:125], v[210:225]
	ds_read_b128 v[186:189], v181 offset:12288
	v_exp_f32_e32 v80, v80
	v_add_f32_e32 v182, v76, v182
	v_exp_f32_e32 v81, v81
	v_add_f32_e32 v182, v77, v182
	s_waitcnt lgkmcnt(5)
	v_mfma_f32_32x32x16_bf16 v[210:225], v[190:193], v[110:113], v[210:225]
	ds_read_b128 v[190:193], v180 offset:12288
	v_add_f32_e32 v182, v78, v182
	v_add_f32_e32 v182, v79, v182
	v_add_f32_e32 v182, v80, v182
	v_add_f32_e32 v182, v81, v182
	s_waitcnt lgkmcnt(5)
	v_mfma_f32_32x32x16_bf16 v[210:225], v[194:197], v[114:117], v[210:225]
	ds_read_b128 v[194:197], v179 offset:12288
	v_cvt_pk_bf16_f32 v66, v66, v67
	v_cvt_pk_bf16_f32 v67, v68, v69
	v_cvt_pk_bf16_f32 v68, v70, v71
	v_cvt_pk_bf16_f32 v69, v72, v73
	s_waitcnt lgkmcnt(5)
	v_mfma_f32_32x32x16_bf16 v[210:225], v[198:201], v[106:109], v[210:225]
	ds_read_b128 v[198:201], v178 offset:12288
	v_cvt_pk_bf16_f32 v70, v74, v75
	v_cvt_pk_bf16_f32 v71, v76, v77
	v_cvt_pk_bf16_f32 v72, v78, v79
	v_cvt_pk_bf16_f32 v73, v80, v81
	s_waitcnt lgkmcnt(5)
	v_mfma_f32_32x32x16_bf16 v[210:225], v[202:205], v[102:105], v[210:225]
	ds_read_b128 v[202:205], v181 offset:12416
	v_permlane32_swap_b32_e32 v66, v68
	v_permlane32_swap_b32_e32 v67, v69
	v_exp_f32_e32 v82, v82
	v_exp_f32_e32 v83, v83
	s_waitcnt lgkmcnt(5)
	v_mfma_f32_32x32x16_bf16 v[210:225], v[206:209], v[98:101], v[210:225]
	ds_read_b128 v[206:209], v180 offset:12416
	v_exp_f32_e32 v84, v84
	v_permlane32_swap_b32_e32 v70, v72
	v_permlane32_swap_b32_e32 v71, v73
	v_exp_f32_e32 v85, v85
	s_waitcnt lgkmcnt(5)
	v_mfma_f32_32x32x16_bf16 v[226:241], v[186:189], v[142:145], 0
	ds_read_b128 v[186:189], v179 offset:12416
	v_exp_f32_e32 v86, v86
	v_add_f32_e32 v182, v82, v182
	v_exp_f32_e32 v87, v87
	v_add_f32_e32 v182, v83, v182
	s_waitcnt lgkmcnt(5)
	v_mfma_f32_32x32x16_bf16 v[226:241], v[190:193], v[138:141], v[226:241]
	ds_read_b128 v[190:193], v178 offset:12416
	v_exp_f32_e32 v88, v88
	v_add_f32_e32 v182, v84, v182
	v_exp_f32_e32 v89, v89
	v_add_f32_e32 v182, v85, v182
	s_waitcnt lgkmcnt(5)
	v_mfma_f32_32x32x16_bf16 v[226:241], v[194:197], v[134:137], v[226:241]
	ds_read_b128 v[194:197], v181 offset:12544
	v_exp_f32_e32 v90, v90
	v_add_f32_e32 v182, v86, v182
	v_exp_f32_e32 v91, v91
	v_add_f32_e32 v182, v87, v182
	s_waitcnt lgkmcnt(5)
	v_mfma_f32_32x32x16_bf16 v[226:241], v[198:201], v[126:129], v[226:241]
	ds_read_b128 v[198:201], v180 offset:12544
	v_exp_f32_e32 v92, v92
	v_add_f32_e32 v182, v88, v182
	v_exp_f32_e32 v93, v93
	v_add_f32_e32 v182, v89, v182
	s_waitcnt lgkmcnt(5)
	v_mfma_f32_32x32x16_bf16 v[226:241], v[202:205], v[130:133], v[226:241]
	ds_read_b128 v[202:205], v179 offset:12544
	v_exp_f32_e32 v94, v94
	v_add_f32_e32 v182, v90, v182
	v_exp_f32_e32 v95, v95
	v_add_f32_e32 v182, v91, v182
	s_waitcnt lgkmcnt(5)
	v_mfma_f32_32x32x16_bf16 v[226:241], v[206:209], v[118:121], v[226:241]
	ds_read_b128 v[206:209], v178 offset:12544
	v_exp_f32_e32 v96, v96
	v_add_f32_e32 v182, v92, v182
	v_exp_f32_e32 v97, v97
	v_add_f32_e32 v182, v93, v182
	s_waitcnt lgkmcnt(5)
	v_mfma_f32_32x32x16_bf16 v[226:241], v[186:189], v[122:125], v[226:241]
	v_add_f32_e32 v182, v94, v182
	v_add_f32_e32 v182, v95, v182
	v_add_f32_e32 v182, v96, v182
	v_add_f32_e32 v182, v97, v182
	s_waitcnt lgkmcnt(4)
	v_mfma_f32_32x32x16_bf16 v[226:241], v[190:193], v[110:113], v[226:241]
	v_cvt_pk_bf16_f32 v74, v82, v83
	v_cvt_pk_bf16_f32 v75, v84, v85
	v_cvt_pk_bf16_f32 v76, v86, v87
	v_cvt_pk_bf16_f32 v77, v88, v89
	s_waitcnt lgkmcnt(3)
	v_mfma_f32_32x32x16_bf16 v[226:241], v[194:197], v[114:117], v[226:241]
	s_waitcnt vmcnt(0) lgkmcnt(0)
	s_barrier
	s_setprio 1
	s_cmp_eq_u32 s62, 1
	s_cbranch_scc1 .Lat7_e_nok
	s_mov_b32 m0, s26
	s_nop 0
	global_load_lds_dwordx4 v152, s[98:99]
	global_load_lds_dwordx4 v154, s[98:99] offset:1024
	global_load_lds_dwordx4 v156, s[98:99] offset:2048
	global_load_lds_dwordx4 v158, s[98:99] offset:3072
	s_mov_b32 m0, s56
	s_nop 0
	global_load_lds_dwordx4 v160, s[98:99]
	global_load_lds_dwordx4 v162, s[98:99] offset:1024
	s_add_u32 s98, s98, 0x6000
	s_addc_u32 s99, s99, 0
; #define SBAR() __builtin_amdgcn_sched_barrier(0)
; #define VISSUE(k0) do { const char* vp_ = Vc + (size_t)(k0) * 256; _Pragma("unroll") for (int e = 0; e < 4; ++e) \
;       __builtin_amdgcn_global_load_lds((const unsigned*)(vp_ + vsrc[e]), (unsigned*)(V_lds + (wu * 4 + e) * 1024), 16, 0, 0); } while (0)
; #define ABAR() do { asm volatile("s_waitcnt vmcnt(0) lgkmcnt(0)" ::: "memory"); __builtin_amdgcn_s_barrier(); } while (0)
; template <int OFF> DEVI s16x4 tr_read(int vb) {
;   s16x4 r; asm volatile("ds_read_b64_tr_b16 %0, %1 offset:%2" : "=&v"(r) : "v"(vb), "i"(OFF) : "memory"); return r;
; }
; template <int D0> DEVI void pv_one(f32x16& od, int vb, bf16x8 pa0, bf16x8 pa1, bf16x8 pa2, bf16x8 pa3) {
;   const s16x4 l0 = tr_read<v_rd_off(D0, 0, 0)>(vb), h0 = tr_read<v_rd_off(D0, 0, 1)>(vb), l1 = tr_read<v_rd_off(D0, 1, 0)>(vb), h1 = tr_read<v_rd_off(D0, 1, 1)>(vb);
;   const s16x4 l2 = tr_read<v_rd_off(D0, 2, 0)>(vb), h2 = tr_read<v_rd_off(D0, 2, 1)>(vb), l3 = tr_read<v_rd_off(D0, 3, 0)>(vb), h3 = tr_read<v_rd_off(D0, 3, 1)>(vb);
;   asm volatile("s_waitcnt lgkmcnt(0)" ::: "memory"); SBAR();
;     ...
;   od = __builtin_amdgcn_mfma_f32_32x32x16_bf16(pa0, PK(l0, h0), od, 0, 0, 0);
;   od = __builtin_amdgcn_mfma_f32_32x32x16_bf16(pa1, PK(l1, h1), od, 0, 0, 0);
;   od = __builtin_amdgcn_mfma_f32_32x32x16_bf16(pa2, PK(l2, h2), od, 0, 0, 0);
;   od = __builtin_amdgcn_mfma_f32_32x32x16_bf16(pa3, PK(l3, h3), od, 0, 0, 0);
;     ...
; }
; template <bool FIXED>
; DEVI void attn_task(const bf16_t* __restrict__ Qb, const bf16_t* __restrict__ Kh, const bf16_t* __restrict__ Vh, bf16_t* __restrict__ Ob, char* lds, float shiftC) {
;     ...
;     pv_one<0>(o[0], vb0, pa0, pa1, pa2, pa3); pv_one<1>(o[1], vb0, pa0, pa1, pa2, pa3);
;     pv_one<2>(o[2], vb0, pa0, pa1, pa2, pa3); pv_one<3>(o[3], vb0, pa0, pa1, pa2, pa3);
;     ABAR();
;     if (j + 1 < NT) VISSUE((j + 1) * 64);
;   }
.Lat7_e_nok:
	v_cvt_pk_bf16_f32 v78, v90, v91
	v_cvt_pk_bf16_f32 v79, v92, v93
	v_cvt_pk_bf16_f32 v80, v94, v95
	ds_read_b64_tr_b16 v[186:187], v176 offset:4096
	ds_read_b64_tr_b16 v[188:189], v176 offset:6144
	ds_read_b64_tr_b16 v[190:191], v176 offset:4608
	ds_read_b64_tr_b16 v[192:193], v176 offset:6656
	v_mfma_f32_32x32x16_bf16 v[226:241], v[198:201], v[106:109], v[226:241]
	v_cvt_pk_bf16_f32 v81, v96, v97
	v_add_f32_e32 v0, v0, v182
	ds_read_b64_tr_b16 v[194:195], v176 offset:0
	ds_read_b64_tr_b16 v[196:197], v176 offset:2048
	ds_read_b64_tr_b16 v[198:199], v176 offset:512
	ds_read_b64_tr_b16 v[200:201], v176 offset:2560
	v_mfma_f32_32x32x16_bf16 v[226:241], v[202:205], v[102:105], v[226:241]
	v_permlane32_swap_b32_e32 v74, v76
	v_permlane32_swap_b32_e32 v75, v77
	ds_read_b64_tr_b16 v[202:203], v176 offset:1024
	ds_read_b64_tr_b16 v[204:205], v176 offset:3072
	v_mfma_f32_32x32x16_bf16 v[226:241], v[206:209], v[98:101], v[226:241]
	v_permlane32_swap_b32_e32 v78, v80
	v_permlane32_swap_b32_e32 v79, v81
	ds_read_b64_tr_b16 v[206:207], v176 offset:1536
	ds_read_b64_tr_b16 v[208:209], v176 offset:3584
	s_waitcnt lgkmcnt(6)
	v_mfma_f32_32x32x16_bf16 v[50:65], v[66:69], v[194:197], v[50:65]
	ds_read_b64_tr_b16 v[194:195], v176 offset:5120
	ds_read_b64_tr_b16 v[196:197], v176 offset:7168
	s_waitcnt lgkmcnt(6)
	v_mfma_f32_32x32x16_bf16 v[34:49], v[66:69], v[198:201], v[34:49]
	ds_read_b64_tr_b16 v[198:199], v176 offset:5632
	ds_read_b64_tr_b16 v[200:201], v176 offset:7680
	s_waitcnt lgkmcnt(6)
	v_mfma_f32_32x32x16_bf16 v[18:33], v[66:69], v[202:205], v[18:33]
	ds_read_b64_tr_b16 v[202:203], v176 offset:8192
	ds_read_b64_tr_b16 v[204:205], v176 offset:10240
	s_waitcnt lgkmcnt(6)
	v_mfma_f32_32x32x16_bf16 v[2:17], v[66:69], v[206:209], v[2:17]
	ds_read_b64_tr_b16 v[206:207], v176 offset:8704
	ds_read_b64_tr_b16 v[208:209], v176 offset:10752
	v_mfma_f32_32x32x16_bf16 v[50:65], v[70:73], v[186:189], v[50:65]
	ds_read_b64_tr_b16 v[186:187], v176 offset:9216
	ds_read_b64_tr_b16 v[188:189], v176 offset:11264
	v_mfma_f32_32x32x16_bf16 v[34:49], v[70:73], v[190:193], v[34:49]
	ds_read_b64_tr_b16 v[190:191], v176 offset:9728
	ds_read_b64_tr_b16 v[192:193], v176 offset:11776
	s_waitcnt lgkmcnt(10)
	v_mfma_f32_32x32x16_bf16 v[18:33], v[70:73], v[194:197], v[18:33]
	ds_read_b64_tr_b16 v[194:195], v176 offset:12288
	ds_read_b64_tr_b16 v[196:197], v176 offset:14336
	s_waitcnt lgkmcnt(10)
	v_mfma_f32_32x32x16_bf16 v[2:17], v[70:73], v[198:201], v[2:17]
	ds_read_b64_tr_b16 v[198:199], v176 offset:12800
	ds_read_b64_tr_b16 v[200:201], v176 offset:14848
	s_waitcnt lgkmcnt(10)
	v_mfma_f32_32x32x16_bf16 v[50:65], v[74:77], v[202:205], v[50:65]
	ds_read_b64_tr_b16 v[202:203], v176 offset:13312
	ds_read_b64_tr_b16 v[204:205], v176 offset:15360
	s_waitcnt lgkmcnt(10)
	v_mfma_f32_32x32x16_bf16 v[34:49], v[74:77], v[206:209], v[34:49]
	ds_read_b64_tr_b16 v[206:207], v176 offset:13824
	ds_read_b64_tr_b16 v[208:209], v176 offset:15872
	s_waitcnt lgkmcnt(10)
	v_mfma_f32_32x32x16_bf16 v[18:33], v[74:77], v[186:189], v[18:33]
	s_waitcnt lgkmcnt(8)
	v_mfma_f32_32x32x16_bf16 v[2:17], v[74:77], v[190:193], v[2:17]
	s_waitcnt lgkmcnt(6)
	v_mfma_f32_32x32x16_bf16 v[50:65], v[78:81], v[194:197], v[50:65]
	s_waitcnt vmcnt(0) lgkmcnt(0)
	s_barrier
	s_setprio 0
	s_mov_b32 m0, s58
	ds_read_b128 v[186:189], v181
	global_load_lds_dwordx4 v242, s[100:101]
	global_load_lds_dwordx4 v150, s[100:101] offset:1024
	global_load_lds_dwordx4 v243, s[100:101] offset:2048
	global_load_lds_dwordx4 v146, s[100:101] offset:3072
	s_add_u32 s100, s100, 0x4000
	s_addc_u32 s101, s101, 0
	ds_read_b128 v[190:193], v180
	ds_read_b128 v[194:197], v179
	v_mfma_f32_32x32x16_bf16 v[34:49], v[78:81], v[198:201], v[34:49]
	ds_read_b128 v[198:201], v178
	v_mfma_f32_32x32x16_bf16 v[18:33], v[78:81], v[202:205], v[18:33]
	ds_read_b128 v[202:205], v181 offset:128
	v_mfma_f32_32x32x16_bf16 v[2:17], v[78:81], v[206:209], v[2:17]
	ds_read_b128 v[206:209], v180 offset:128
	s_add_i32 s62, s62, -1
	s_cmp_eq_u32 s62, 0
	s_cbranch_scc1 .Lat7_done
	s_waitcnt lgkmcnt(5)
	v_mfma_f32_32x32x16_bf16 v[66:81], v[186:189], v[142:145], 0
	ds_read_b128 v[186:189], v179 offset:128
	v_exp_f32_e32 v210, v210
	v_exp_f32_e32 v211, v211
	v_exp_f32_e32 v212, v212
	v_exp_f32_e32 v213, v213
	s_waitcnt lgkmcnt(5)
	v_mfma_f32_32x32x16_bf16 v[66:81], v[190:193], v[138:141], v[66:81]
	ds_read_b128 v[190:193], v178 offset:128
	v_exp_f32_e32 v214, v214
	v_add_f32_e32 v182, 0, v210
	v_exp_f32_e32 v215, v215
	v_add_f32_e32 v182, v211, v182
	s_waitcnt lgkmcnt(5)
	v_mfma_f32_32x32x16_bf16 v[66:81], v[194:197], v[134:137], v[66:81]
	ds_read_b128 v[194:197], v181 offset:256
	v_exp_f32_e32 v216, v216
	v_add_f32_e32 v182, v212, v182
	v_exp_f32_e32 v217, v217
	v_add_f32_e32 v182, v213, v182
	s_waitcnt lgkmcnt(5)
	v_mfma_f32_32x32x16_bf16 v[66:81], v[198:201], v[126:129], v[66:81]
	ds_read_b128 v[198:201], v180 offset:256
	v_exp_f32_e32 v218, v218
	v_add_f32_e32 v182, v214, v182
	v_exp_f32_e32 v219, v219
	v_add_f32_e32 v182, v215, v182
	s_waitcnt lgkmcnt(5)
	v_mfma_f32_32x32x16_bf16 v[66:81], v[202:205], v[130:133], v[66:81]
	ds_read_b128 v[202:205], v179 offset:256
	v_exp_f32_e32 v220, v220
	v_add_f32_e32 v182, v216, v182
	v_exp_f32_e32 v221, v221
	v_add_f32_e32 v182, v217, v182
	s_waitcnt lgkmcnt(5)
	v_mfma_f32_32x32x16_bf16 v[66:81], v[206:209], v[118:121], v[66:81]
	ds_read_b128 v[206:209], v178 offset:256
	v_exp_f32_e32 v222, v222
	v_add_f32_e32 v182, v218, v182
	v_exp_f32_e32 v223, v223
	v_add_f32_e32 v182, v219, v182
	s_waitcnt lgkmcnt(5)
; #define KISSUE(k0) do { const char* kp_ = Kc + (size_t)(k0) * 384; _Pragma("unroll") for (int e = 0; e < 6; ++e) \
;       __builtin_amdgcn_global_load_lds((const unsigned*)(kp_ + ksrc[e]), (unsigned*)(K_lds + (wu * 6 + e) * 1024), 16, 0, 0); } while (0)
; #define ABAR() do { asm volatile("s_waitcnt vmcnt(0) lgkmcnt(0)" ::: "memory"); __builtin_amdgcn_s_barrier(); } while (0)
; DEVI void finishSM(f32x16& p0, f32x16& p1, float alpha, float& l_reg, bf16x8& pa0, bf16x8& pa1, bf16x8& pa2, bf16x8& pa3) {
;   float ps = 0;
; #pragma unroll
;   for (int r = 0; r < 16; ++r) ps += p0[r];
; #pragma unroll
;   for (int r = 0; r < 16; ++r) ps += p1[r];
;   { auto rr = __builtin_amdgcn_permlane32_swap(__float_as_uint(ps), __float_as_uint(ps), false, false);
;     ps = __uint_as_float(rr[0]) + __uint_as_float(rr[1]); }
;   l_reg = l_reg * alpha + ps;
;     ...
;   PK4(p0, 0, pa0); PK4(p0, 8, pa1); PK4(p1, 0, pa2); PK4(p1, 8, pa3);
; template <bool FIXED>
; DEVI void attn_task(const bf16_t* __restrict__ Qb, const bf16_t* __restrict__ Kh, const bf16_t* __restrict__ Vh, bf16_t* __restrict__ Ob, char* lds, float shiftC) {
;     ...
;   for (int j = 0; j < NT; ++j) {
;     f32x16 p0 = {}, p1 = {};
; #pragma unroll
;     for (int d0 = 0; d0 < 12; ++d0) {
;       const bf16x8 b0 = *(const bf16x8*)(Kr0 + (d0 >> 2) * 128 + kx[d0 & 3]);
;       const bf16x8 b1 = *(const bf16x8*)(Kr0 + 32 * 384 + (d0 >> 2) * 128 + kx[d0 & 3]);
;       p0 = __builtin_amdgcn_mfma_f32_32x32x16_bf16(b0, qr[d0], p0, 0, 0, 0);
;       p1 = __builtin_amdgcn_mfma_f32_32x32x16_bf16(b1, qr[d0], p1, 0, 0, 0);
;     }
;     ABAR();
;     if (j + 1 < NT) KISSUE((j + 1) * 64);
;     float mn, alpha = 1.f;
;     if constexpr (FIXED) {
; #pragma unroll
;       for (int r = 0; r < 16; ++r) p0[r] = __builtin_amdgcn_exp2f(p0[r]);
; #pragma unroll
;       for (int r = 0; r < 16; ++r) p1[r] = __builtin_amdgcn_exp2f(p1[r]);
	v_mfma_f32_32x32x16_bf16 v[66:81], v[186:189], v[122:125], v[66:81]
	ds_read_b128 v[186:189], v181 offset:12288
	v_exp_f32_e32 v224, v224
	v_add_f32_e32 v182, v220, v182
	v_exp_f32_e32 v225, v225
	v_add_f32_e32 v182, v221, v182
	s_waitcnt lgkmcnt(5)
	v_mfma_f32_32x32x16_bf16 v[66:81], v[190:193], v[110:113], v[66:81]
	ds_read_b128 v[190:193], v180 offset:12288
	v_add_f32_e32 v182, v222, v182
	v_add_f32_e32 v182, v223, v182
	v_add_f32_e32 v182, v224, v182
	v_add_f32_e32 v182, v225, v182
	s_waitcnt lgkmcnt(5)
	v_mfma_f32_32x32x16_bf16 v[66:81], v[194:197], v[114:117], v[66:81]
	ds_read_b128 v[194:197], v179 offset:12288
	v_cvt_pk_bf16_f32 v210, v210, v211
	v_cvt_pk_bf16_f32 v211, v212, v213
	v_cvt_pk_bf16_f32 v212, v214, v215
	v_cvt_pk_bf16_f32 v213, v216, v217
	s_waitcnt lgkmcnt(5)
	v_mfma_f32_32x32x16_bf16 v[66:81], v[198:201], v[106:109], v[66:81]
	ds_read_b128 v[198:201], v178 offset:12288
	v_cvt_pk_bf16_f32 v214, v218, v219
	v_cvt_pk_bf16_f32 v215, v220, v221
	v_cvt_pk_bf16_f32 v216, v222, v223
	v_cvt_pk_bf16_f32 v217, v224, v225
	s_waitcnt lgkmcnt(5)
	v_mfma_f32_32x32x16_bf16 v[66:81], v[202:205], v[102:105], v[66:81]
	ds_read_b128 v[202:205], v181 offset:12416
	v_permlane32_swap_b32_e32 v210, v212
	v_permlane32_swap_b32_e32 v211, v213
	v_exp_f32_e32 v226, v226
	v_exp_f32_e32 v227, v227
	s_waitcnt lgkmcnt(5)
	v_mfma_f32_32x32x16_bf16 v[66:81], v[206:209], v[98:101], v[66:81]
	ds_read_b128 v[206:209], v180 offset:12416
	v_exp_f32_e32 v228, v228
	v_permlane32_swap_b32_e32 v214, v216
	v_permlane32_swap_b32_e32 v215, v217
	v_exp_f32_e32 v229, v229
	s_waitcnt lgkmcnt(5)
	v_mfma_f32_32x32x16_bf16 v[82:97], v[186:189], v[142:145], 0
	ds_read_b128 v[186:189], v179 offset:12416
	v_exp_f32_e32 v230, v230
	v_add_f32_e32 v182, v226, v182
	v_exp_f32_e32 v231, v231
	v_add_f32_e32 v182, v227, v182
	s_waitcnt lgkmcnt(5)
	v_mfma_f32_32x32x16_bf16 v[82:97], v[190:193], v[138:141], v[82:97]
	ds_read_b128 v[190:193], v178 offset:12416
	v_exp_f32_e32 v232, v232
	v_add_f32_e32 v182, v228, v182
	v_exp_f32_e32 v233, v233
	v_add_f32_e32 v182, v229, v182
	s_waitcnt lgkmcnt(5)
	v_mfma_f32_32x32x16_bf16 v[82:97], v[194:197], v[134:137], v[82:97]
	ds_read_b128 v[194:197], v181 offset:12544
	v_exp_f32_e32 v234, v234
	v_add_f32_e32 v182, v230, v182
	v_exp_f32_e32 v235, v235
	v_add_f32_e32 v182, v231, v182
	s_waitcnt lgkmcnt(5)
	v_mfma_f32_32x32x16_bf16 v[82:97], v[198:201], v[126:129], v[82:97]
	ds_read_b128 v[198:201], v180 offset:12544
	v_exp_f32_e32 v236, v236
	v_add_f32_e32 v182, v232, v182
	v_exp_f32_e32 v237, v237
	v_add_f32_e32 v182, v233, v182
	s_waitcnt lgkmcnt(5)
	v_mfma_f32_32x32x16_bf16 v[82:97], v[202:205], v[130:133], v[82:97]
	ds_read_b128 v[202:205], v179 offset:12544
	v_exp_f32_e32 v238, v238
	v_add_f32_e32 v182, v234, v182
	v_exp_f32_e32 v239, v239
	v_add_f32_e32 v182, v235, v182
	s_waitcnt lgkmcnt(5)
	v_mfma_f32_32x32x16_bf16 v[82:97], v[206:209], v[118:121], v[82:97]
	ds_read_b128 v[206:209], v178 offset:12544
	v_exp_f32_e32 v240, v240
	v_add_f32_e32 v182, v236, v182
	v_exp_f32_e32 v241, v241
	v_add_f32_e32 v182, v237, v182
	s_waitcnt lgkmcnt(5)
	v_mfma_f32_32x32x16_bf16 v[82:97], v[186:189], v[122:125], v[82:97]
	v_add_f32_e32 v182, v238, v182
	v_add_f32_e32 v182, v239, v182
	v_add_f32_e32 v182, v240, v182
	v_add_f32_e32 v182, v241, v182
	s_waitcnt lgkmcnt(4)
	v_mfma_f32_32x32x16_bf16 v[82:97], v[190:193], v[110:113], v[82:97]
	v_cvt_pk_bf16_f32 v218, v226, v227
	v_cvt_pk_bf16_f32 v219, v228, v229
	v_cvt_pk_bf16_f32 v220, v230, v231
	v_cvt_pk_bf16_f32 v221, v232, v233
	s_waitcnt lgkmcnt(3)
	v_mfma_f32_32x32x16_bf16 v[82:97], v[194:197], v[114:117], v[82:97]
	s_waitcnt vmcnt(0) lgkmcnt(0)
	s_barrier
; #define SBAR() __builtin_amdgcn_sched_barrier(0)
; DEVI int crow(int r, int hi) { return (r & 3) + 8 * (r >> 2) + 4 * hi; }
; template <int OFF> DEVI s16x4 tr_read(int vb) {
;   s16x4 r; asm volatile("ds_read_b64_tr_b16 %0, %1 offset:%2" : "=&v"(r) : "v"(vb), "i"(OFF) : "memory"); return r;
; }
; template <int D0> DEVI void pv_one(f32x16& od, int vb, bf16x8 pa0, bf16x8 pa1, bf16x8 pa2, bf16x8 pa3) {
;   const s16x4 l0 = tr_read<v_rd_off(D0, 0, 0)>(vb), h0 = tr_read<v_rd_off(D0, 0, 1)>(vb), l1 = tr_read<v_rd_off(D0, 1, 0)>(vb), h1 = tr_read<v_rd_off(D0, 1, 1)>(vb);
;   const s16x4 l2 = tr_read<v_rd_off(D0, 2, 0)>(vb), h2 = tr_read<v_rd_off(D0, 2, 1)>(vb), l3 = tr_read<v_rd_off(D0, 3, 0)>(vb), h3 = tr_read<v_rd_off(D0, 3, 1)>(vb);
;   asm volatile("s_waitcnt lgkmcnt(0)" ::: "memory"); SBAR();
;     ...
;   od = __builtin_amdgcn_mfma_f32_32x32x16_bf16(pa0, PK(l0, h0), od, 0, 0, 0);
;   od = __builtin_amdgcn_mfma_f32_32x32x16_bf16(pa1, PK(l1, h1), od, 0, 0, 0);
;   od = __builtin_amdgcn_mfma_f32_32x32x16_bf16(pa2, PK(l2, h2), od, 0, 0, 0);
;   od = __builtin_amdgcn_mfma_f32_32x32x16_bf16(pa3, PK(l3, h3), od, 0, 0, 0);
;     ...
; }
; template <bool FIXED>
; DEVI void attn_task(const bf16_t* __restrict__ Qb, const bf16_t* __restrict__ Kh, const bf16_t* __restrict__ Vh, bf16_t* __restrict__ Ob, char* lds, float shiftC) {
;     ...
;     ABAR();
;     if (j + 1 < NT) KISSUE((j + 1) * 64);
;     float mn, alpha = 1.f;
;     if constexpr (FIXED) {
; #pragma unroll
;       for (int r = 0; r < 16; ++r) p0[r] = __builtin_amdgcn_exp2f(p0[r]);
; #pragma unroll
;       for (int r = 0; r < 16; ++r) p1[r] = __builtin_amdgcn_exp2f(p1[r]);
;     } else partialSM(p0, p1, m_reg, mn, alpha);
;     if (!FIXED && __any(alpha < 1.f)) {
;       if (hi == 0) al_l[r32] = alpha;
;       asm volatile("s_waitcnt lgkmcnt(0)" ::: "memory");
; #pragma unroll
;       for (int r = 0; r < 16; ++r) { const float a = al_l[crow(r, hi)];
; #pragma unroll
;         for (int d = 0; d < 4; ++d) o[d][r] *= a; }
;     }
;     bf16x8 pa0, pa1, pa2, pa3;
;     finishSM(p0, p1, alpha, l_reg, pa0, pa1, pa2, pa3);
;     pv_one<0>(o[0], vb0, pa0, pa1, pa2, pa3); pv_one<1>(o[1], vb0, pa0, pa1, pa2, pa3);
;     pv_one<2>(o[2], vb0, pa0, pa1, pa2, pa3); pv_one<3>(o[3], vb0, pa0, pa1, pa2, pa3);
;     ABAR();
;     if (j + 1 < NT) VISSUE((j + 1) * 64);
;   }
	s_setprio 1
	s_mov_b32 m0, s26
	s_nop 0
	global_load_lds_dwordx4 v152, s[98:99]
	global_load_lds_dwordx4 v154, s[98:99] offset:1024
	global_load_lds_dwordx4 v156, s[98:99] offset:2048
	global_load_lds_dwordx4 v158, s[98:99] offset:3072
	s_mov_b32 m0, s56
	s_nop 0
	global_load_lds_dwordx4 v160, s[98:99]
	global_load_lds_dwordx4 v162, s[98:99] offset:1024
	s_add_u32 s98, s98, 0x6000
	s_addc_u32 s99, s99, 0
	v_cvt_pk_bf16_f32 v222, v234, v235
	v_cvt_pk_bf16_f32 v223, v236, v237
	v_cvt_pk_bf16_f32 v224, v238, v239
	ds_read_b64_tr_b16 v[186:187], v176 offset:4096
	ds_read_b64_tr_b16 v[188:189], v176 offset:6144
	ds_read_b64_tr_b16 v[190:191], v176 offset:4608
	ds_read_b64_tr_b16 v[192:193], v176 offset:6656
	v_mfma_f32_32x32x16_bf16 v[82:97], v[198:201], v[106:109], v[82:97]
	v_cvt_pk_bf16_f32 v225, v240, v241
	v_add_f32_e32 v0, v0, v182
	ds_read_b64_tr_b16 v[194:195], v176 offset:0
	ds_read_b64_tr_b16 v[196:197], v176 offset:2048
	ds_read_b64_tr_b16 v[198:199], v176 offset:512
	ds_read_b64_tr_b16 v[200:201], v176 offset:2560
	v_mfma_f32_32x32x16_bf16 v[82:97], v[202:205], v[102:105], v[82:97]
	v_permlane32_swap_b32_e32 v218, v220
	v_permlane32_swap_b32_e32 v219, v221
	ds_read_b64_tr_b16 v[202:203], v176 offset:1024
	ds_read_b64_tr_b16 v[204:205], v176 offset:3072
	v_mfma_f32_32x32x16_bf16 v[82:97], v[206:209], v[98:101], v[82:97]
	v_permlane32_swap_b32_e32 v222, v224
	v_permlane32_swap_b32_e32 v223, v225
	ds_read_b64_tr_b16 v[206:207], v176 offset:1536
	ds_read_b64_tr_b16 v[208:209], v176 offset:3584
	s_waitcnt lgkmcnt(6)
	v_mfma_f32_32x32x16_bf16 v[50:65], v[210:213], v[194:197], v[50:65]
	ds_read_b64_tr_b16 v[194:195], v176 offset:5120
	ds_read_b64_tr_b16 v[196:197], v176 offset:7168
	s_waitcnt lgkmcnt(6)
	v_mfma_f32_32x32x16_bf16 v[34:49], v[210:213], v[198:201], v[34:49]
	ds_read_b64_tr_b16 v[198:199], v176 offset:5632
	ds_read_b64_tr_b16 v[200:201], v176 offset:7680
	s_waitcnt lgkmcnt(6)
	v_mfma_f32_32x32x16_bf16 v[18:33], v[210:213], v[202:205], v[18:33]
	ds_read_b64_tr_b16 v[202:203], v176 offset:8192
	ds_read_b64_tr_b16 v[204:205], v176 offset:10240
	s_waitcnt lgkmcnt(6)
	v_mfma_f32_32x32x16_bf16 v[2:17], v[210:213], v[206:209], v[2:17]
	ds_read_b64_tr_b16 v[206:207], v176 offset:8704
	ds_read_b64_tr_b16 v[208:209], v176 offset:10752
	v_mfma_f32_32x32x16_bf16 v[50:65], v[214:217], v[186:189], v[50:65]
	ds_read_b64_tr_b16 v[186:187], v176 offset:9216
	ds_read_b64_tr_b16 v[188:189], v176 offset:11264
	v_mfma_f32_32x32x16_bf16 v[34:49], v[214:217], v[190:193], v[34:49]
	ds_read_b64_tr_b16 v[190:191], v176 offset:9728
	ds_read_b64_tr_b16 v[192:193], v176 offset:11776
	s_waitcnt lgkmcnt(10)
	v_mfma_f32_32x32x16_bf16 v[18:33], v[214:217], v[194:197], v[18:33]
	ds_read_b64_tr_b16 v[194:195], v176 offset:12288
	ds_read_b64_tr_b16 v[196:197], v176 offset:14336
	s_waitcnt lgkmcnt(10)
	v_mfma_f32_32x32x16_bf16 v[2:17], v[214:217], v[198:201], v[2:17]
	ds_read_b64_tr_b16 v[198:199], v176 offset:12800
	ds_read_b64_tr_b16 v[200:201], v176 offset:14848
	s_waitcnt lgkmcnt(10)
	v_mfma_f32_32x32x16_bf16 v[50:65], v[218:221], v[202:205], v[50:65]
	ds_read_b64_tr_b16 v[202:203], v176 offset:13312
	ds_read_b64_tr_b16 v[204:205], v176 offset:15360
	s_waitcnt lgkmcnt(10)
	v_mfma_f32_32x32x16_bf16 v[34:49], v[218:221], v[206:209], v[34:49]
	ds_read_b64_tr_b16 v[206:207], v176 offset:13824
	ds_read_b64_tr_b16 v[208:209], v176 offset:15872
	s_waitcnt lgkmcnt(10)
	v_mfma_f32_32x32x16_bf16 v[18:33], v[218:221], v[186:189], v[18:33]
	s_waitcnt lgkmcnt(8)
	v_mfma_f32_32x32x16_bf16 v[2:17], v[218:221], v[190:193], v[2:17]
	s_waitcnt lgkmcnt(6)
	v_mfma_f32_32x32x16_bf16 v[50:65], v[222:225], v[194:197], v[50:65]
	s_waitcnt vmcnt(0) lgkmcnt(0)
	s_barrier
	s_setprio 0
	s_mov_b32 m0, s58
	ds_read_b128 v[186:189], v181
	global_load_lds_dwordx4 v242, s[100:101]
	global_load_lds_dwordx4 v150, s[100:101] offset:1024
	global_load_lds_dwordx4 v243, s[100:101] offset:2048
	global_load_lds_dwordx4 v146, s[100:101] offset:3072
	s_add_u32 s100, s100, 0x4000
	s_addc_u32 s101, s101, 0
	ds_read_b128 v[190:193], v180
	ds_read_b128 v[194:197], v179
	v_mfma_f32_32x32x16_bf16 v[34:49], v[222:225], v[198:201], v[34:49]
	ds_read_b128 v[198:201], v178
	v_mfma_f32_32x32x16_bf16 v[18:33], v[222:225], v[202:205], v[18:33]
	ds_read_b128 v[202:205], v181 offset:128
	v_mfma_f32_32x32x16_bf16 v[2:17], v[222:225], v[206:209], v[2:17]
	ds_read_b128 v[206:209], v180 offset:128
	s_add_i32 s62, s62, -1
	s_branch .Lat7_top
